# grid barrier: non-leader workgroups poll TOPGEN directly (no XGEN relay); P1 epilogue stores write-through (sc1)
# baseline (speedup 1.0000x reference)
.Lp1pf_done:
	s_cmpk_gt_i32 s37, 0x4a3
	s_waitcnt vmcnt(14)
	v_mul_f32_e32 v120, v120, v130
	v_mul_f32_e32 v121, v121, v130
	v_mul_f32_e32 v117, v117, v130
	v_mul_f32_e32 v122, v122, v130
	v_mul_f32_e32 v123, v123, v130
	v_mul_f32_e32 v124, v124, v130
	v_mul_f32_e32 v101, v101, v137
	v_mul_f32_e32 v118, v118, v130
	v_mul_f32_e32 v119, v119, v130
	v_mul_f32_e32 v145, v114, v130
	v_mul_f32_e32 v146, v115, v130
	v_mul_f32_e32 v147, v116, v130
	v_mul_f32_e32 v125, v125, v130
	v_cvt_pk_bf16_f32 v114, v118, v119
	v_cvt_pk_bf16_f32 v115, v120, v121
	v_cvt_pk_bf16_f32 v116, v145, v146
	v_cvt_pk_bf16_f32 v117, v147, v117
	v_cvt_pk_bf16_f32 v120, v122, v123
	v_cvt_pk_bf16_f32 v121, v124, v125
	v_mul_f32_e32 v102, v102, v137
	v_mul_f32_e32 v103, v103, v137
	v_mul_f32_e32 v104, v104, v137
	v_mul_f32_e32 v105, v105, v137
	v_mul_f32_e32 v122, v98, v137
	v_mul_f32_e32 v123, v99, v137
	v_mul_f32_e32 v124, v100, v137
	v_cvt_pk_bf16_f32 v98, v102, v103
	v_cvt_pk_bf16_f32 v99, v104, v105
	v_cvt_pk_bf16_f32 v100, v122, v123
	v_cvt_pk_bf16_f32 v101, v124, v101
	v_mul_f32_e32 v126, v126, v130
	v_mul_f32_e32 v127, v127, v130
	v_mul_f32_e32 v128, v128, v130
	v_mul_f32_e32 v129, v129, v130
	v_cvt_pk_bf16_f32 v118, v126, v127
	v_cvt_pk_bf16_f32 v119, v128, v129
	v_mul_f32_e32 v110, v110, v137
	v_mul_f32_e32 v111, v111, v137
	v_mul_f32_e32 v112, v112, v137
	v_mul_f32_e32 v113, v113, v137
	v_mul_f32_e32 v106, v106, v137
	v_mul_f32_e32 v107, v107, v137
	v_mul_f32_e32 v108, v108, v137
	v_mul_f32_e32 v109, v109, v137
	global_store_dwordx4 v[142:143], v[114:117], off sc1
	global_store_dwordx4 v[142:143], v[118:121], off offset:256 sc1
	v_cvt_pk_bf16_f32 v102, v110, v111
	v_cvt_pk_bf16_f32 v103, v112, v113
	v_cvt_pk_bf16_f32 v104, v106, v107
	v_cvt_pk_bf16_f32 v105, v108, v109
	global_store_dwordx4 v[140:141], v[98:101], off sc1
	global_store_dwordx4 v[140:141], v[102:105], off offset:256 sc1
	v_or_b32_e32 v98, 48, v136
	v_ashrrev_i32_e32 v99, 31, v98
	v_lshl_add_u64 v[100:101], v[98:99], 2, s[2:3]
	v_or_b32_e32 v99, 32, v136
	v_add_u32_e32 v100, 0x80, v136
	v_mad_i64_i32 v[102:103], s[22:23], v99, s36, v[132:133]
	v_mad_i64_i32 v[98:99], s[22:23], v98, s36, v[132:133]
	v_ashrrev_i32_e32 v101, 31, v100
	v_lshl_add_u64 v[102:103], v[102:103], 0, v[134:135]
	v_lshl_add_u64 v[98:99], v[98:99], 0, v[134:135]
	v_lshl_add_u64 v[104:105], v[100:101], 2, s[2:3]
	s_waitcnt vmcnt(16)
	v_mul_f32_e32 v78, v78, v150
	v_mul_f32_e32 v79, v79, v150
	v_mul_f32_e32 v80, v80, v150
	v_mul_f32_e32 v81, v81, v150
	v_mul_f32_e32 v74, v74, v150
	v_mul_f32_e32 v75, v75, v150
	v_mul_f32_e32 v76, v76, v150
	v_mul_f32_e32 v77, v77, v150
	s_waitcnt vmcnt(16)
	v_mul_f32_e32 v110, v66, v151
	v_mul_f32_e32 v111, v67, v151
	v_mul_f32_e32 v112, v68, v151
	v_mul_f32_e32 v113, v69, v151
	v_cvt_pk_bf16_f32 v66, v78, v79
	v_cvt_pk_bf16_f32 v67, v80, v81
	v_cvt_pk_bf16_f32 v68, v74, v75
	v_cvt_pk_bf16_f32 v69, v76, v77
	v_mul_f32_e32 v94, v94, v150
	v_mul_f32_e32 v95, v95, v150
	v_mul_f32_e32 v96, v96, v150
	v_mul_f32_e32 v97, v97, v150
	v_mul_f32_e32 v90, v90, v150
	v_mul_f32_e32 v91, v91, v150
	v_mul_f32_e32 v92, v92, v150
	v_mul_f32_e32 v93, v93, v150
	v_mul_f32_e32 v101, v70, v151
	v_mul_f32_e32 v106, v71, v151
	v_mul_f32_e32 v108, v72, v151
	v_mul_f32_e32 v109, v73, v151
	v_mul_f32_e32 v86, v86, v151
	v_mul_f32_e32 v87, v87, v151
	v_mul_f32_e32 v88, v88, v151
	v_mul_f32_e32 v89, v89, v151
	v_mul_f32_e32 v82, v82, v151
	v_mul_f32_e32 v83, v83, v151
	v_mul_f32_e32 v84, v84, v151
	v_mul_f32_e32 v85, v85, v151
	v_cvt_pk_bf16_f32 v70, v94, v95
	v_cvt_pk_bf16_f32 v71, v96, v97
	v_cvt_pk_bf16_f32 v72, v90, v91
	v_cvt_pk_bf16_f32 v73, v92, v93
	v_cvt_pk_bf16_f32 v74, v101, v106
	v_cvt_pk_bf16_f32 v75, v108, v109
	v_cvt_pk_bf16_f32 v76, v110, v111
	v_cvt_pk_bf16_f32 v77, v112, v113
	v_cvt_pk_bf16_f32 v78, v86, v87
	v_cvt_pk_bf16_f32 v79, v88, v89
	v_cvt_pk_bf16_f32 v80, v82, v83
	v_cvt_pk_bf16_f32 v81, v84, v85
	global_store_dwordx4 v[102:103], v[66:69], off sc1
	global_store_dwordx4 v[102:103], v[70:73], off offset:256 sc1
	global_store_dwordx4 v[98:99], v[74:77], off sc1
	global_store_dwordx4 v[98:99], v[78:81], off offset:256 sc1
	v_add_u32_e32 v66, 0x90, v136
	v_ashrrev_i32_e32 v67, 31, v66
	v_lshl_add_u64 v[68:69], v[66:67], 2, s[2:3]
	v_add_u32_e32 v68, 0xa0, v136
	v_mad_i64_i32 v[70:71], s[22:23], v100, s36, v[132:133]
	v_mad_i64_i32 v[66:67], s[22:23], v66, s36, v[132:133]
	v_ashrrev_i32_e32 v69, 31, v68
	v_lshl_add_u64 v[70:71], v[70:71], 0, v[134:135]
	v_lshl_add_u64 v[66:67], v[66:67], 0, v[134:135]
	v_lshl_add_u64 v[72:73], v[68:69], 2, s[2:3]
	s_waitcnt vmcnt(18)
	v_mul_f32_e32 v54, v54, v152
	v_mul_f32_e32 v55, v55, v152
	v_mul_f32_e32 v56, v56, v152
	v_mul_f32_e32 v57, v57, v152
	v_mul_f32_e32 v46, v46, v152
	v_mul_f32_e32 v47, v47, v152
	v_mul_f32_e32 v48, v48, v152
	v_mul_f32_e32 v49, v49, v152
	s_waitcnt vmcnt(18)
	v_mul_f32_e32 v78, v34, v153
	v_mul_f32_e32 v79, v35, v153
	v_mul_f32_e32 v80, v36, v153
	v_mul_f32_e32 v81, v37, v153
	v_cvt_pk_bf16_f32 v34, v54, v55
	v_cvt_pk_bf16_f32 v35, v56, v57
	v_cvt_pk_bf16_f32 v36, v46, v47
	v_cvt_pk_bf16_f32 v37, v48, v49
	v_mul_f32_e32 v62, v62, v152
	v_mul_f32_e32 v63, v63, v152
	v_mul_f32_e32 v64, v64, v152
	v_mul_f32_e32 v65, v65, v152
	v_mul_f32_e32 v58, v58, v152
	v_mul_f32_e32 v59, v59, v152
	v_mul_f32_e32 v60, v60, v152
	v_mul_f32_e32 v61, v61, v152
	v_mul_f32_e32 v69, v38, v153
	v_mul_f32_e32 v74, v39, v153
	v_mul_f32_e32 v76, v40, v153
	v_mul_f32_e32 v77, v41, v153
	v_mul_f32_e32 v50, v50, v153
	v_mul_f32_e32 v51, v51, v153
	v_mul_f32_e32 v52, v52, v153
	v_mul_f32_e32 v53, v53, v153
	v_mul_f32_e32 v82, v42, v153
	v_mul_f32_e32 v83, v43, v153
	v_mul_f32_e32 v84, v44, v153
	v_mul_f32_e32 v75, v45, v153
	v_cvt_pk_bf16_f32 v38, v62, v63
	v_cvt_pk_bf16_f32 v39, v64, v65
	v_cvt_pk_bf16_f32 v40, v58, v59
	v_cvt_pk_bf16_f32 v41, v60, v61
	v_cvt_pk_bf16_f32 v42, v69, v74
	v_cvt_pk_bf16_f32 v43, v76, v77
	v_cvt_pk_bf16_f32 v44, v78, v79
	v_cvt_pk_bf16_f32 v45, v80, v81
	v_cvt_pk_bf16_f32 v46, v50, v51
	v_cvt_pk_bf16_f32 v47, v52, v53
	v_cvt_pk_bf16_f32 v48, v82, v83
	v_cvt_pk_bf16_f32 v49, v84, v75
	global_store_dwordx4 v[70:71], v[34:37], off sc1
	global_store_dwordx4 v[70:71], v[38:41], off offset:256 sc1
	global_store_dwordx4 v[66:67], v[42:45], off sc1
	global_store_dwordx4 v[66:67], v[46:49], off offset:256 sc1
	v_add_u32_e32 v34, 0xb0, v136
	v_ashrrev_i32_e32 v35, 31, v34
	v_lshl_add_u64 v[36:37], v[34:35], 2, s[2:3]
	v_mad_i64_i32 v[36:37], s[22:23], v68, s36, v[132:133]
	v_mad_i64_i32 v[34:35], s[22:23], v34, s36, v[132:133]
	v_lshl_add_u64 v[36:37], v[36:37], 0, v[134:135]
	v_lshl_add_u64 v[34:35], v[34:35], 0, v[134:135]
	s_waitcnt vmcnt(20)
	v_mul_f32_e32 v22, v22, v154
	v_mul_f32_e32 v23, v23, v154
	v_mul_f32_e32 v24, v24, v154
	v_mul_f32_e32 v25, v25, v154
	v_mul_f32_e32 v14, v14, v154
	v_mul_f32_e32 v15, v15, v154
	v_mul_f32_e32 v16, v16, v154
	v_mul_f32_e32 v17, v17, v154
	s_waitcnt vmcnt(20)
	v_mul_f32_e32 v43, v2, v155
	v_mul_f32_e32 v44, v3, v155
	v_mul_f32_e32 v45, v4, v155
	v_mul_f32_e32 v46, v5, v155
	v_cvt_pk_bf16_f32 v2, v22, v23
	v_cvt_pk_bf16_f32 v3, v24, v25
	v_cvt_pk_bf16_f32 v4, v14, v15
	v_cvt_pk_bf16_f32 v5, v16, v17
	v_mul_f32_e32 v30, v30, v154
	v_mul_f32_e32 v31, v31, v154
	v_mul_f32_e32 v32, v32, v154
	v_mul_f32_e32 v33, v33, v154
	v_mul_f32_e32 v26, v26, v154
	v_mul_f32_e32 v27, v27, v154
	v_mul_f32_e32 v28, v28, v154
	v_mul_f32_e32 v29, v29, v154
	v_mul_f32_e32 v38, v6, v155
	v_mul_f32_e32 v40, v7, v155
	v_mul_f32_e32 v41, v8, v155
	v_mul_f32_e32 v42, v9, v155
	v_mul_f32_e32 v18, v18, v155
	v_mul_f32_e32 v19, v19, v155
	v_mul_f32_e32 v20, v20, v155
	v_mul_f32_e32 v21, v21, v155
	v_mul_f32_e32 v47, v10, v155
	v_mul_f32_e32 v48, v11, v155
	v_mul_f32_e32 v49, v12, v155
	v_mul_f32_e32 v39, v13, v155
	v_cvt_pk_bf16_f32 v6, v30, v31
	v_cvt_pk_bf16_f32 v7, v32, v33
	v_cvt_pk_bf16_f32 v8, v26, v27
	v_cvt_pk_bf16_f32 v9, v28, v29
	v_cvt_pk_bf16_f32 v10, v38, v40
	v_cvt_pk_bf16_f32 v11, v41, v42
	v_cvt_pk_bf16_f32 v12, v43, v44
	v_cvt_pk_bf16_f32 v13, v45, v46
	v_cvt_pk_bf16_f32 v14, v18, v19
	v_cvt_pk_bf16_f32 v15, v20, v21
	v_cvt_pk_bf16_f32 v16, v47, v48
	v_cvt_pk_bf16_f32 v17, v49, v39
	global_store_dwordx4 v[36:37], v[2:5], off sc1
	global_store_dwordx4 v[36:37], v[6:9], off offset:256 sc1
	global_store_dwordx4 v[34:35], v[10:13], off sc1
	global_store_dwordx4 v[34:35], v[14:17], off offset:256 sc1
	s_barrier
	s_cbranch_scc1 .LBB0_120

.Lpppf_skip:
	v_cvt_pk_bf16_f32 v122, v122, v123
	v_cvt_pk_bf16_f32 v123, v124, v125
	v_cvt_pk_bf16_f32 v124, v114, v115
	v_lshlrev_b64 v[114:115], 11, v[132:133]
	v_ashrrev_i32_e32 v137, 31, v136
	v_cvt_pk_bf16_f32 v125, v116, v117
	v_lshl_add_u64 v[116:117], s[2:3], 0, v[114:115]
	v_lshlrev_b64 v[114:115], 1, v[136:137]
	v_cvt_pk_bf16_f32 v102, v102, v103
	v_cvt_pk_bf16_f32 v103, v104, v105
	v_cvt_pk_bf16_f32 v104, v98, v99
	v_lshlrev_b64 v[98:99], 11, v[138:139]
	v_lshl_add_u64 v[136:137], v[116:117], 0, v[114:115]
	v_cvt_pk_bf16_f32 v116, v126, v127
	v_cvt_pk_bf16_f32 v117, v128, v129
	v_lshl_add_u64 v[98:99], s[2:3], 0, v[98:99]
	v_cvt_pk_bf16_f32 v118, v118, v119
	v_cvt_pk_bf16_f32 v119, v120, v121
	global_store_dwordx4 v[136:137], v[116:119], off offset:256 sc1
	v_cvt_pk_bf16_f32 v105, v100, v101
	v_cvt_pk_bf16_f32 v100, v106, v107
	v_cvt_pk_bf16_f32 v101, v108, v109
	v_cvt_pk_bf16_f32 v86, v86, v87
	v_cvt_pk_bf16_f32 v87, v88, v89
	s_nop 1
	v_lshl_add_u64 v[116:117], v[98:99], 0, v[114:115]
	v_cvt_pk_bf16_f32 v98, v110, v111
	v_cvt_pk_bf16_f32 v99, v112, v113
	global_store_dwordx4 v[116:117], v[98:101], off offset:256 sc1
	v_cvt_pk_bf16_f32 v88, v82, v83
	v_cvt_pk_bf16_f32 v70, v70, v71
	v_cvt_pk_bf16_f32 v71, v72, v73
	v_cvt_pk_bf16_f32 v72, v58, v59
	v_cvt_pk_bf16_f32 v89, v84, v85
	s_nop 1
	v_or_b32_e32 v100, 32, v132
	v_or_b32_e32 v98, 48, v132
	v_ashrrev_i32_e32 v101, 31, v100
	v_ashrrev_i32_e32 v99, 31, v98
	v_lshlrev_b64 v[82:83], 11, v[100:101]
	v_lshl_add_u64 v[82:83], s[2:3], 0, v[82:83]
	v_lshlrev_b64 v[58:59], 11, v[98:99]
	v_lshl_add_u64 v[100:101], v[82:83], 0, v[114:115]
	v_cvt_pk_bf16_f32 v82, v94, v95
	v_cvt_pk_bf16_f32 v83, v96, v97
	v_lshl_add_u64 v[58:59], s[2:3], 0, v[58:59]
	v_cvt_pk_bf16_f32 v84, v90, v91
	v_cvt_pk_bf16_f32 v85, v92, v93
	global_store_dwordx4 v[100:101], v[82:85], off offset:256 sc1
	v_cvt_pk_bf16_f32 v73, v60, v61
	v_cvt_pk_bf16_f32 v46, v46, v47
	v_cvt_pk_bf16_f32 v47, v48, v49
	v_cvt_pk_bf16_f32 v49, v40, v41
	v_cvt_pk_bf16_f32 v40, v34, v35
	s_nop 1
	v_lshl_add_u64 v[82:83], v[58:59], 0, v[114:115]
	global_store_dwordx4 v[82:83], v[70:73], off sc1
	v_cvt_pk_bf16_f32 v41, v36, v37
	v_add_u32_e32 v34, 0xb0, v132
	v_add_u32_e32 v36, 0xa0, v132
	v_add_u32_e32 v70, 0x80, v132
	v_add_u32_e32 v72, 0x90, v132
	v_cvt_pk_bf16_f32 v60, v74, v75
	v_ashrrev_i32_e32 v73, 31, v72
	v_ashrrev_i32_e32 v71, 31, v70
	v_ashrrev_i32_e32 v35, 31, v34
	v_ashrrev_i32_e32 v37, 31, v36
	v_cvt_pk_bf16_f32 v58, v78, v79
	v_cvt_pk_bf16_f32 v59, v80, v81
	v_cvt_pk_bf16_f32 v61, v76, v77
	global_store_dwordx4 v[82:83], v[58:61], off offset:256 sc1
	v_cvt_pk_bf16_f32 v48, v38, v39
	v_lshlrev_b64 v[38:39], 11, v[72:73]
	v_cvt_pk_bf16_f32 v30, v30, v31
	v_cvt_pk_bf16_f32 v31, v32, v33
	v_cvt_pk_bf16_f32 v32, v22, v23
	s_nop 0
	v_cvt_pk_bf16_f32 v60, v54, v55
	v_lshlrev_b64 v[54:55], 11, v[70:71]
	v_lshlrev_b64 v[22:23], 11, v[36:37]
	v_cvt_pk_bf16_f32 v14, v14, v15
	v_cvt_pk_bf16_f32 v15, v16, v17
	v_cvt_pk_bf16_f32 v16, v6, v7
	v_lshlrev_b64 v[6:7], 11, v[34:35]
	v_lshl_add_u64 v[54:55], s[2:3], 0, v[54:55]
	v_lshl_add_u64 v[38:39], s[2:3], 0, v[38:39]
	v_lshl_add_u64 v[22:23], s[2:3], 0, v[22:23]
	v_lshl_add_u64 v[6:7], s[2:3], 0, v[6:7]
	s_add_i32 s18, s18, s97
	v_cvt_pk_bf16_f32 v58, v66, v67
	v_cvt_pk_bf16_f32 v61, v56, v57
	v_lshl_add_u64 v[66:67], v[54:55], 0, v[114:115]
	v_cvt_pk_bf16_f32 v56, v50, v51
	v_lshl_add_u64 v[50:51], v[38:39], 0, v[114:115]
	v_cvt_pk_bf16_f32 v33, v24, v25
	v_lshl_add_u64 v[36:37], v[22:23], 0, v[114:115]
	v_cvt_pk_bf16_f32 v24, v18, v19
	v_lshl_add_u64 v[18:19], v[6:7], 0, v[114:115]
	s_cmpk_gt_i32 s18, 0x107
	global_store_dwordx4 v[136:137], v[122:125], off sc1
	global_store_dwordx4 v[116:117], v[102:105], off sc1
	global_store_dwordx4 v[100:101], v[86:89], off sc1
	v_cvt_pk_bf16_f32 v59, v68, v69
	global_store_dwordx4 v[66:67], v[58:61], off sc1
	v_cvt_pk_bf16_f32 v54, v62, v63
	v_cvt_pk_bf16_f32 v55, v64, v65
	v_cvt_pk_bf16_f32 v57, v52, v53
	global_store_dwordx4 v[66:67], v[54:57], off offset:256 sc1
	global_store_dwordx4 v[50:51], v[46:49], off sc1
	v_cvt_pk_bf16_f32 v38, v42, v43
	v_cvt_pk_bf16_f32 v39, v44, v45
	global_store_dwordx4 v[50:51], v[38:41], off offset:256 sc1
	global_store_dwordx4 v[36:37], v[30:33], off sc1
	v_cvt_pk_bf16_f32 v22, v26, v27
	v_cvt_pk_bf16_f32 v23, v28, v29
	v_cvt_pk_bf16_f32 v25, v20, v21
	global_store_dwordx4 v[36:37], v[22:25], off offset:256 sc1
	v_cvt_pk_bf16_f32 v17, v8, v9
	global_store_dwordx4 v[18:19], v[14:17], off sc1
	v_cvt_pk_bf16_f32 v6, v10, v11
	v_cvt_pk_bf16_f32 v7, v12, v13
	v_cvt_pk_bf16_f32 v8, v2, v3
	v_cvt_pk_bf16_f32 v9, v4, v5
	global_store_dwordx4 v[18:19], v[6:9], off offset:256 sc1
	s_barrier
	s_cbranch_scc1 .LBB0_127
